# phase 1: static work shift to the first-slot workgroups (15 GEMM passes each, second-slot 12-13), moved items stay on their XCD
# speedup vs baseline: 1.0109x; 1.0050x over previous
.LBB0_211:
	s_load_dword s0, s[66:67], 0x0
	s_waitcnt lgkmcnt(0)
	s_cmp_eq_u32 s0, 0x200
	s_cbranch_scc0 .Lx1_orig
	s_add_i32 s89, s89, 0x200
	s_sub_i32 s1, s89, s2
	s_cmp_lt_u32 s2, 64
	s_cbranch_scc0 .Lx1_a
	s_cmpk_lt_i32 s1, 0x1200
	s_cbranch_scc1 .LBB0_212
	s_branch .LBB0_281
.Lx1_a:
	s_cmp_lt_u32 s2, 0x98
	s_cbranch_scc0 .Lx1_b
	s_and_b32 s0, s1, 0x1ff
	s_cmp_lg_u32 s0, 0
	s_cbranch_scc1 .LBB0_281
	s_cmpk_lt_i32 s1, 0x1400
	s_cbranch_scc1 .LBB0_212
	s_add_i32 s89, s2, 0x1190
	s_cmp_lt_u32 s2, 88
	s_cbranch_scc1 .LBB0_212
	s_add_i32 s89, s2, 0x11a8
	s_branch .LBB0_212
.Lx1_b:
	s_cmp_lt_u32 s2, 0x100
	s_cbranch_scc0 .Lx1_c
	s_cmpk_lt_i32 s1, 0x1200
	s_cbranch_scc1 .LBB0_212
	s_add_i32 s89, s2, 0x1068
	s_cmpk_eq_i32 s1, 0x1200
	s_cbranch_scc1 .LBB0_212
	s_add_i32 s89, s2, 0x10d0
	s_cmpk_eq_i32 s1, 0x1268
	s_cbranch_scc1 .LBB0_212
	s_branch .LBB0_281
.Lx1_c:
	s_cmp_lt_u32 s2, 0x1e8
	s_cbranch_scc0 .Lx1_norm
	s_cmpk_lt_i32 s1, 0x1000
	s_cbranch_scc1 .LBB0_212
	s_branch .LBB0_281
.Lx1_norm:
	s_cmpk_lt_i32 s89, 0x1298
	s_cbranch_scc1 .LBB0_212
	s_branch .LBB0_281
.Lx1_orig:
	s_add_i32 s89, s0, s89
	s_cmpk_lt_i32 s89, 0x1298
	s_cbranch_scc0 .LBB0_281
